# adds: HGRN2 stage-2c and NA ds_read2_b64 split into ds_read_b64 (LDS rate / bank conflicts), HGRN2 stage-3 LDS reads hoisted ahead of MFMAs through a ring of spare VGPRs
# speedup vs baseline: 1.0082x; 1.0082x over previous
.LBB0_283:
	v_cmp_le_i32_e32 vcc, v87, v91
	s_waitcnt lgkmcnt(2)
	v_pk_mul_f32 v[20:21], v[52:53], v[20:21]
	v_mul_lo_u32 v52, v177, s81
	s_nop 1
	v_cndmask_b32_e32 v48, 0, v48, vcc
	v_cmp_lt_i32_e32 vcc, v87, v91
	v_lshlrev_b32_e32 v53, 1, v86
	v_pk_mul_f32 v[44:45], v[72:73], v[44:45]
	v_cndmask_b32_e32 v49, 0, v49, vcc
	v_cmp_le_i32_e32 vcc, v88, v91
	v_cvt_pk_bf16_f32 v48, v48, v49
	v_add3_u32 v72, 0, v52, v53
	v_cndmask_b32_e32 v50, 0, v50, vcc
	v_cmp_le_i32_e32 vcc, v89, v91
	v_pk_mul_f32 v[22:23], v[54:55], v[22:23]
	v_pk_mul_f32 v[46:47], v[74:75], v[46:47]
	v_cndmask_b32_e32 v51, 0, v51, vcc
	v_cvt_pk_bf16_f32 v49, v50, v51
	v_mul_lo_u32 v50, v91, s82
	v_add3_u32 v50, s83, v50, v90
	ds_write_b64 v50, v[48:49]
	ds_read_b64 v[52:53], v72
	ds_read_b64 v[54:55], v72 offset:32
	v_add_u32_e32 v73, 0x1000, v72
	v_add_u32_e32 v74, 0x2000, v72
	v_add_u32_e32 v75, 0x3000, v72
	v_pk_mul_f32 v[34:35], v[66:67], v[34:35]
	v_pk_mul_f32 v[32:33], v[64:65], v[32:33]
	v_pk_mul_f32 v[30:31], v[62:63], v[30:31]
	v_pk_mul_f32 v[28:29], v[60:61], v[28:29]
	v_pk_mul_f32 v[26:27], v[58:59], v[26:27]
	v_pk_mul_f32 v[24:25], v[56:57], v[24:25]
	ds_read_b64 v[56:57], v73 offset:512
	ds_read_b64 v[58:59], v73 offset:544
	ds_read_b64 v[60:61], v74 offset:1024
	ds_read_b64 v[62:63], v74 offset:1056
	ds_read_b64 v[64:65], v75 offset:1536
	ds_read_b64 v[66:67], v75 offset:1568
	v_pk_mul_f32 v[38:39], v[70:71], v[38:39]
	v_pk_mul_f32 v[36:37], v[68:69], v[36:37]
	ds_read_b64 v[68:69], v72 offset:64
	ds_read_b64 v[70:71], v72 offset:96
	v_pk_mul_f32 v[42:43], v[78:79], v[42:43]
	v_pk_mul_f32 v[40:41], v[76:77], v[40:41]
	v_cvt_pk_bf16_f32 v49, v42, v43
	v_cvt_pk_bf16_f32 v48, v40, v41
	v_cvt_pk_bf16_f32 v50, v44, v45
	v_cvt_pk_bf16_f32 v51, v46, v47
	s_waitcnt lgkmcnt(12)
	v_pk_mul_f32 v[18:19], v[82:83], v[18:19]
	v_pk_mul_f32 v[16:17], v[80:81], v[16:17]
	s_waitcnt lgkmcnt(8)
	v_mfma_f32_16x16x32_bf16 v[52:55], v[52:55], v[48:51], 0
	v_lshlrev_b32_e32 v85, 3, v100
	v_mul_lo_u32 v76, v177, s82
	v_add_u32_e32 v80, 0xa00, v76
	s_waitcnt lgkmcnt(6)
	v_mfma_f32_16x16x32_bf16 v[56:59], v[56:59], v[48:51], 0
	v_add_u32_e32 v87, 0x1400, v76
	v_add_u32_e32 v88, 0x1e00, v76
	v_add_u32_e32 v99, v84, v76
	s_waitcnt lgkmcnt(4)
	v_mfma_f32_16x16x32_bf16 v[60:63], v[60:63], v[48:51], 0
	v_add_u32_e32 v112, v84, v80
	v_add_u32_e32 v113, v84, v87
	v_add_u32_e32 v114, v84, v88
	s_waitcnt lgkmcnt(2)
	v_mfma_f32_16x16x32_bf16 v[48:51], v[64:67], v[48:51], 0
	v_cvt_pk_bf16_f32 v64, v36, v37
	v_cvt_pk_bf16_f32 v65, v38, v39
	v_cvt_pk_bf16_f32 v66, v32, v33
	v_cvt_pk_bf16_f32 v67, v34, v35
	s_movk_i32 s8, 0x840
	s_and_b64 vcc, exec, s[6:7]
	s_waitcnt lgkmcnt(0)
	v_mfma_f32_16x16x32_bf16 v[52:55], v[68:71], v[64:67], v[52:55]
	ds_read_b64 v[68:69], v73 offset:576
	ds_read_b64 v[70:71], v73 offset:608
	s_waitcnt lgkmcnt(0)
	v_mfma_f32_16x16x32_bf16 v[56:59], v[68:71], v[64:67], v[56:59]
	ds_read_b64 v[68:69], v74 offset:1088
	ds_read_b64 v[70:71], v74 offset:1120
	s_waitcnt lgkmcnt(0)
	v_mfma_f32_16x16x32_bf16 v[60:63], v[68:71], v[64:67], v[60:63]
	ds_read_b64 v[68:69], v75 offset:1600
	ds_read_b64 v[70:71], v75 offset:1632
	s_waitcnt lgkmcnt(0)
	v_mfma_f32_16x16x32_bf16 v[48:51], v[68:71], v[64:67], v[48:51]
	ds_read_b64 v[68:69], v72 offset:128
	ds_read_b64 v[70:71], v72 offset:160
	v_cvt_pk_bf16_f32 v64, v28, v29
	v_cvt_pk_bf16_f32 v65, v30, v31
	v_cvt_pk_bf16_f32 v66, v24, v25
	v_cvt_pk_bf16_f32 v67, v26, v27
	s_waitcnt lgkmcnt(0)
	s_nop 0
	v_mfma_f32_16x16x32_bf16 v[52:55], v[68:71], v[64:67], v[52:55]
	ds_read_b64 v[68:69], v73 offset:640
	ds_read_b64 v[70:71], v73 offset:672
	s_waitcnt lgkmcnt(0)
	v_mfma_f32_16x16x32_bf16 v[56:59], v[68:71], v[64:67], v[56:59]
	ds_read_b64 v[68:69], v74 offset:1152
	ds_read_b64 v[70:71], v74 offset:1184
	s_waitcnt lgkmcnt(0)
	v_mfma_f32_16x16x32_bf16 v[60:63], v[68:71], v[64:67], v[60:63]
	ds_read_b64 v[68:69], v75 offset:1664
	ds_read_b64 v[70:71], v75 offset:1696
	s_waitcnt lgkmcnt(0)
	v_mfma_f32_16x16x32_bf16 v[48:51], v[68:71], v[64:67], v[48:51]
	ds_read_b64 v[68:69], v72 offset:192
	ds_read_b64 v[70:71], v72 offset:224
	v_cvt_pk_bf16_f32 v64, v20, v21
	v_cvt_pk_bf16_f32 v65, v22, v23
	v_cvt_pk_bf16_f32 v66, v16, v17
	v_cvt_pk_bf16_f32 v67, v18, v19
	s_waitcnt lgkmcnt(0)
	s_nop 0
	v_mfma_f32_16x16x32_bf16 v[52:55], v[68:71], v[64:67], v[52:55]
	ds_read_b64 v[68:69], v73 offset:704
	ds_read_b64 v[70:71], v73 offset:736
	s_waitcnt lgkmcnt(0)
	v_mfma_f32_16x16x32_bf16 v[56:59], v[68:71], v[64:67], v[56:59]
	ds_read_b64 v[68:69], v74 offset:1216
	ds_read_b64 v[70:71], v74 offset:1248
	s_waitcnt lgkmcnt(0)
	v_mfma_f32_16x16x32_bf16 v[60:63], v[68:71], v[64:67], v[60:63]
	ds_read_b64 v[68:69], v75 offset:1728
	ds_read_b64 v[70:71], v75 offset:1760
	s_waitcnt lgkmcnt(0)
	s_barrier
	s_waitcnt lgkmcnt(0)
	v_mfma_f32_16x16x32_bf16 v[48:51], v[68:71], v[64:67], v[48:51]
	v_add_u32_e32 v64, s12, v177
	v_lshlrev_b32_e32 v65, 1, v85
	v_mul_lo_u32 v64, v64, s82
	v_add_u32_e32 v72, s83, v65
	v_add3_u32 v85, 0, v64, v65
	v_add_u32_e32 v86, v72, v76
	v_add_u32_e32 v90, v72, v80
	v_add_u32_e32 v94, v72, v87
	v_add_u32_e32 v98, v72, v88
	ds_read_b128 v[240:243], v85 offset:57344
	ds_read_b128 v[208:211], v86
	ds_read_b128 v[212:215], v90
	ds_read_b128 v[216:219], v94
	ds_read_b128 v[220:223], v98
	ds_read_b128 v[224:227], v99 offset:36864
	ds_read_b128 v[228:231], v112 offset:36864
	ds_read_b128 v[232:235], v113 offset:36864
	ds_read_b128 v[236:239], v114 offset:36864
	s_waitcnt lgkmcnt(7)
	v_mfma_f32_16x16x32_bf16 v[68:71], v[208:211], v[240:243], v[52:55]
	ds_read_b128 v[208:211], v99 offset:47104
	s_waitcnt lgkmcnt(7)
	v_mfma_f32_16x16x32_bf16 v[56:59], v[212:215], v[240:243], v[56:59]
	ds_read_b128 v[212:215], v99 offset:49664
	s_waitcnt lgkmcnt(7)
	v_mfma_f32_16x16x32_bf16 v[60:63], v[216:219], v[240:243], v[60:63]
	ds_read_b128 v[216:219], v99 offset:52224
	s_waitcnt lgkmcnt(7)
	v_mfma_f32_16x16x32_bf16 v[72:75], v[220:223], v[240:243], v[48:51]
	ds_read_b128 v[220:223], v99 offset:54784
	s_waitcnt lgkmcnt(7)
	v_mfma_f32_16x16x32_bf16 v[76:79], v[224:227], v[240:243], v[40:43]
	ds_read_b128 v[244:247], v85 offset:57408
	ds_read_b128 v[224:227], v86 offset:64
	s_waitcnt lgkmcnt(8)
	v_mfma_f32_16x16x32_bf16 v[80:83], v[228:231], v[240:243], v[44:47]
	ds_read_b128 v[228:231], v114 offset:36928
	s_waitcnt lgkmcnt(8)
	v_mfma_f32_16x16x32_bf16 v[52:55], v[232:235], v[240:243], v[36:39]
	ds_read_b128 v[232:235], v90 offset:64
	s_waitcnt lgkmcnt(8)
	v_mfma_f32_16x16x32_bf16 v[48:51], v[236:239], v[240:243], v[32:35]
	ds_read_b128 v[236:239], v99 offset:47168
	s_waitcnt lgkmcnt(8)
	v_mfma_f32_16x16x32_bf16 v[32:35], v[208:211], v[240:243], v[28:31]
	ds_read_b128 v[208:211], v94 offset:64
	s_waitcnt lgkmcnt(8)
	v_mfma_f32_16x16x32_bf16 v[36:39], v[212:215], v[240:243], v[24:27]
	ds_read_b128 v[212:215], v99 offset:49728
	s_waitcnt lgkmcnt(8)
	v_mfma_f32_16x16x32_bf16 v[40:43], v[216:219], v[240:243], v[20:23]
	ds_read_b128 v[216:219], v98 offset:64
	s_waitcnt lgkmcnt(8)
	v_mfma_f32_16x16x32_bf16 v[44:47], v[220:223], v[240:243], v[16:19]
	ds_read_b128 v[220:223], v99 offset:52288
	s_waitcnt lgkmcnt(7)
	v_mfma_f32_16x16x32_bf16 v[86:89], v[224:227], v[244:247], v[68:71]
	ds_read_b128 v[224:227], v112 offset:36928
	s_waitcnt lgkmcnt(7)
	v_mfma_f32_16x16x32_bf16 v[28:31], v[228:231], v[244:247], v[48:51]
	ds_read_b128 v[228:231], v99 offset:54848
	s_waitcnt lgkmcnt(7)
	v_mfma_f32_16x16x32_bf16 v[90:93], v[232:235], v[244:247], v[56:59]
	ds_read_b128 v[232:235], v99 offset:36928
	s_waitcnt lgkmcnt(7)
	v_mfma_f32_16x16x32_bf16 v[32:35], v[236:239], v[244:247], v[32:35]
	ds_read_b128 v[236:239], v113 offset:36928
	s_waitcnt lgkmcnt(7)
	v_mfma_f32_16x16x32_bf16 v[94:97], v[208:211], v[244:247], v[60:63]
	s_waitcnt lgkmcnt(6)
	v_mfma_f32_16x16x32_bf16 v[36:39], v[212:215], v[244:247], v[36:39]
	s_waitcnt lgkmcnt(5)
	v_mfma_f32_16x16x32_bf16 v[108:111], v[216:219], v[244:247], v[72:75]
	s_waitcnt lgkmcnt(4)
	v_mfma_f32_16x16x32_bf16 v[40:43], v[220:223], v[244:247], v[40:43]
	s_waitcnt lgkmcnt(3)
	v_mfma_f32_16x16x32_bf16 v[20:23], v[224:227], v[244:247], v[80:83]
	s_waitcnt lgkmcnt(2)
	v_mfma_f32_16x16x32_bf16 v[44:47], v[228:231], v[244:247], v[44:47]
	s_waitcnt lgkmcnt(1)
	v_mfma_f32_16x16x32_bf16 v[16:19], v[232:235], v[244:247], v[76:79]
	s_waitcnt lgkmcnt(0)
	v_mfma_f32_16x16x32_bf16 v[24:27], v[236:239], v[244:247], v[52:55]
	v_lshlrev_b32_e32 v80, 2, v177
	v_mul_lo_u32 v81, v100, s8
	v_add3_u32 v80, s14, v80, v81
	v_add_u32_e32 v48, 0x1ea00, v84
	v_add_u32_e32 v81, 0x400, v80
	s_movk_i32 s8, 0x210
	s_nop 1
	ds_read_b128 v[76:79], v48
	ds_read_b128 v[72:75], v48 offset:64
	ds_read_b128 v[68:71], v48 offset:128
	ds_read_b128 v[64:67], v48 offset:192
	ds_read_b128 v[60:63], v48 offset:256
	ds_read_b128 v[56:59], v48 offset:320
	ds_read_b128 v[52:55], v48 offset:384
	ds_read_b128 v[48:51], v48 offset:448
	ds_write2_b32 v81, v88, v89 offset0:8 offset1:140
	v_add_u32_e32 v81, 0x2000, v80
	ds_write2_b32 v81, v90, v91 offset0:64 offset1:196
	v_add_u32_e32 v81, 0x2400, v80
	ds_write2_b32 v81, v92, v93 offset0:72 offset1:204
	v_add_u32_e32 v81, 0x4200, v80
	ds_write2_b32 v81, v94, v95 offset1:132
	v_add_u32_e32 v81, 0x4600, v80
	ds_write2_b32 v80, v86, v87 offset1:132
	ds_write2_b32 v81, v96, v97 offset0:8 offset1:140
	v_add_u32_e32 v81, 0x6200, v80
	v_add_u32_e32 v80, 0x6600, v80
	ds_write2_b32 v81, v108, v109 offset0:64 offset1:196
	ds_write2_b32 v80, v110, v111 offset0:72 offset1:204
	v_mul_lo_u32 v80, v189, s8
	v_lshlrev_b32_e32 v81, 2, v188
	s_waitcnt lgkmcnt(0)
	s_barrier
	v_add3_u32 v80, 0, v80, v81
	ds_read_b128 v[92:95], v80
	ds_read_b128 v[88:91], v80 offset:16
	ds_read_b128 v[84:87], v80 offset:32
	ds_read_b128 v[80:83], v80 offset:48
	s_cbranch_vccz .LBB0_288
	s_mov_b64 s[36:37], 0
	s_and_b64 vcc, exec, s[0:1]
	s_mov_b64 s[38:39], 0
	s_cbranch_vccz .LBB0_286
	s_waitcnt vmcnt(26)
	v_lshlrev_b32_e32 v96, 16, v12
	v_and_b32_e32 v97, 0xffff0000, v12
	v_lshlrev_b32_e32 v12, 16, v13
	v_and_b32_e32 v13, 0xffff0000, v13
	s_waitcnt lgkmcnt(3)
	v_pk_add_f32 v[116:117], v[94:95], v[12:13]
	v_lshlrev_b32_e32 v12, 16, v14
	v_and_b32_e32 v13, 0xffff0000, v14
	s_waitcnt lgkmcnt(2)
	v_pk_add_f32 v[118:119], v[88:89], v[12:13]
	v_lshlrev_b32_e32 v12, 16, v8
	v_and_b32_e32 v13, 0xffff0000, v8
	v_lshlrev_b32_e32 v8, 16, v9
	v_and_b32_e32 v9, 0xffff0000, v9
	v_pk_add_f32 v[114:115], v[92:93], v[96:97]
	s_waitcnt lgkmcnt(1)
	v_pk_add_f32 v[190:191], v[86:87], v[8:9]
	v_lshlrev_b32_e32 v8, 16, v10
	v_and_b32_e32 v9, 0xffff0000, v10
	v_lshlrev_b32_e32 v10, 16, v11
	v_and_b32_e32 v11, 0xffff0000, v11
	v_lshlrev_b32_e32 v14, 16, v15
	v_and_b32_e32 v15, 0xffff0000, v15
	s_waitcnt lgkmcnt(0)
	v_pk_add_f32 v[194:195], v[82:83], v[10:11]
	v_pk_add_f32 v[196:197], v[80:81], v[8:9]
	v_pk_mul_f32 v[8:9], v[116:117], v[116:117]
	v_pk_mul_f32 v[10:11], v[114:115], v[114:115]
	v_pk_add_f32 v[120:121], v[90:91], v[14:15]
	v_pk_add_f32 v[192:193], v[84:85], v[12:13]
	v_pk_mov_b32 v[12:13], v[10:11], v[8:9] op_sel:[1,0]
	v_mov_b32_e32 v11, v9
	v_pk_add_f32 v[8:9], v[12:13], v[10:11]
	v_pk_mul_f32 v[10:11], v[120:121], v[120:121]
	v_pk_mul_f32 v[12:13], v[118:119], v[118:119]
	v_pk_add_f32 v[8:9], v[8:9], v[8:9] op_sel:[0,1] op_sel_hi:[1,0]
	v_pk_mov_b32 v[14:15], v[12:13], v[10:11] op_sel:[1,0]
	v_mov_b32_e32 v13, v11
	v_pk_add_f32 v[10:11], v[14:15], v[12:13]
	v_mul_f32_e32 v12, v196, v196
	v_mul_f32_e32 v13, v197, v197
	v_pk_add_f32 v[10:11], v[10:11], v[10:11] op_sel:[0,1] op_sel_hi:[1,0]
	v_mov_b32_e32 v9, v12
	v_mov_b32_e32 v11, v13
	v_pk_add_f32 v[8:9], v[8:9], v[10:11]
	v_mul_f32_e32 v10, v193, v193
	v_mul_f32_e32 v12, v191, v191
	v_mul_f32_e32 v14, v194, v194
	v_mul_f32_e32 v15, v195, v195
	v_pk_fma_f32 v[10:11], v[192:193], v[192:193], v[10:11] op_sel_hi:[1,1,0]
	v_pk_fma_f32 v[12:13], v[190:191], v[190:191], v[12:13] op_sel_hi:[1,1,0]
	v_mov_b32_e32 v11, v14
	v_mov_b32_e32 v13, v15
	v_pk_add_f32 v[10:11], v[10:11], v[12:13]
	s_mov_b64 s[38:39], -1
	v_pk_add_f32 v[8:9], v[8:9], v[10:11]
	s_nop 0
	v_add_f32_e32 v8, v8, v9
	s_nop 1
	v_add_f32_dpp v8, v8, v8 quad_perm:[1,0,3,2] row_mask:0xf bank_mask:0xf bound_ctrl:1
	s_nop 1
	v_add_f32_dpp v8, v8, v8 quad_perm:[2,3,0,1] row_mask:0xf bank_mask:0xf bound_ctrl:1
	s_nop 1
	v_add_f32_dpp v8, v8, v8 row_half_mirror row_mask:0xf bank_mask:0xf bound_ctrl:1
	v_fmamk_f32 v8, v8, 0x3c000000, v160
	v_rsq_f32_e32 v198, v8
	v_mul_lo_u32 v8, v182, s80
	v_add_lshl_u32 v100, v8, v188, 1
	v_lshl_add_u32 v8, v188, 2, 0
	v_add_u32_e32 v110, 0x20000, v8
	ds_read_b128 v[8:11], v110
	ds_read_b128 v[12:15], v110 offset:16
	ds_read_b128 v[96:99], v110 offset:32
	ds_read_b128 v[110:113], v110 offset:48
	v_pk_mul_f32 v[114:115], v[114:115], v[198:199] op_sel_hi:[1,0]
	v_lshl_add_u64 v[108:109], s[34:35], 0, v[100:101]
	s_waitcnt lgkmcnt(3)
	v_pk_mul_f32 v[8:9], v[8:9], v[114:115]
	s_waitcnt vmcnt(24)
	v_lshlrev_b32_e32 v114, 16, v4
	v_and_b32_e32 v115, 0xffff0000, v4
	v_pk_mul_f32 v[8:9], v[8:9], v[114:115]
	v_pk_mul_f32 v[114:115], v[116:117], v[198:199] op_sel_hi:[1,0]
	v_lshlrev_b32_e32 v4, 16, v5
	v_pk_mul_f32 v[10:11], v[10:11], v[114:115]
	v_and_b32_e32 v5, 0xffff0000, v5
	v_pk_mul_f32 v[10:11], v[10:11], v[4:5]
	v_pk_mul_f32 v[4:5], v[118:119], v[198:199] op_sel_hi:[1,0]
	s_waitcnt lgkmcnt(2)
	v_pk_mul_f32 v[4:5], v[12:13], v[4:5]
	v_lshlrev_b32_e32 v12, 16, v6
	v_and_b32_e32 v13, 0xffff0000, v6
	v_pk_mul_f32 v[12:13], v[4:5], v[12:13]
	v_pk_mul_f32 v[4:5], v[120:121], v[198:199] op_sel_hi:[1,0]
	v_lshlrev_b32_e32 v6, 16, v7
	v_pk_mul_f32 v[4:5], v[14:15], v[4:5]
	v_and_b32_e32 v7, 0xffff0000, v7
	v_pk_mul_f32 v[14:15], v[4:5], v[6:7]
	v_cvt_pk_bf16_f32 v4, v8, v9
	v_cvt_pk_bf16_f32 v5, v10, v11
	v_cvt_pk_bf16_f32 v6, v12, v13
	v_cvt_pk_bf16_f32 v7, v14, v15
	global_store_dwordx4 v100, v[4:7], s[34:35]
	v_lshlrev_b32_e32 v8, 16, v2
	v_and_b32_e32 v9, 0xffff0000, v2
	v_pk_mul_f32 v[4:5], v[192:193], v[198:199] op_sel_hi:[1,0]
	v_lshlrev_b32_e32 v6, 16, v0
	s_waitcnt lgkmcnt(1)
	v_pk_mul_f32 v[4:5], v[96:97], v[4:5]
	v_and_b32_e32 v7, 0xffff0000, v0
	v_pk_mul_f32 v[4:5], v[4:5], v[6:7]
	v_pk_mul_f32 v[6:7], v[190:191], v[198:199] op_sel_hi:[1,0]
	v_lshlrev_b32_e32 v0, 16, v1
	v_pk_mul_f32 v[6:7], v[98:99], v[6:7]
	v_and_b32_e32 v1, 0xffff0000, v1
	v_pk_mul_f32 v[0:1], v[6:7], v[0:1]
	v_pk_mul_f32 v[6:7], v[196:197], v[198:199] op_sel_hi:[1,0]
	v_lshlrev_b32_e32 v2, 16, v3
	s_waitcnt lgkmcnt(0)
	v_pk_mul_f32 v[6:7], v[6:7], v[110:111]
	v_and_b32_e32 v3, 0xffff0000, v3
	v_pk_mul_f32 v[6:7], v[6:7], v[8:9]
	v_pk_mul_f32 v[8:9], v[194:195], v[198:199] op_sel_hi:[1,0]
	v_cvt_pk_bf16_f32 v96, v4, v5
	v_pk_mul_f32 v[8:9], v[8:9], v[112:113]
	v_cvt_pk_bf16_f32 v97, v0, v1
	v_pk_mul_f32 v[110:111], v[8:9], v[2:3]
	v_cvt_pk_bf16_f32 v98, v6, v7
	s_and_b64 vcc, exec, s[36:37]
	s_cbranch_vccz .LBB0_289
	s_branch .LBB0_287

.LBB0_1752:
	v_add_f32_e32 v2, v161, v162
	v_fmamk_f32 v2, v2, 0x3d000000, v142
	v_rsq_f32_e32 v2, v2
	s_movk_i32 s8, 0xab
	s_add_i32 s9, s58, 0xfffd
	s_and_b32 s20, s9, 0xff
	v_mul_f32_e32 v2, 0x3e8293ee, v2
	v_pk_mul_f32 v[4:5], v[2:3], v[138:139] op_sel_hi:[0,1]
	v_pk_mul_f32 v[6:7], v[2:3], v[136:137] op_sel_hi:[0,1]
	v_pk_mul_f32 v[8:9], v[2:3], v[134:135] op_sel_hi:[0,1]
	v_pk_mul_f32 v[2:3], v[2:3], v[132:133] op_sel_hi:[0,1]
	s_waitcnt lgkmcnt(0)
	v_pk_mul_f32 v[18:19], v[120:121], v[2:3]
	v_mul_lo_u32 v2, v160, s8
	v_bfe_u32 v2, v2, 11, 5
	v_mul_lo_u32 v2, v2, 12
	v_sub_u32_e32 v2, v160, v2
	v_lshlrev_b32_sdwa v69, v146, v2 dst_sel:DWORD dst_unused:UNUSED_PAD src0_sel:DWORD src1_sel:BYTE_0
	s_mulk_i32 s20, 0xab
	v_add_u32_e32 v74, s59, v69
	s_lshr_b32 s20, s20, 11
	v_add_u32_e32 v2, v74, v148
	s_mul_i32 s20, s20, 12
	v_mad_i32_i24 v2, v2, s42, v153
	s_add_i32 s8, s57, 8
	s_sub_i32 s9, s9, s20
	v_pk_mul_f32 v[14:15], v[124:125], v[6:7]
	v_pk_mul_f32 v[16:17], v[118:119], v[8:9]
	ds_read_b128 v[6:9], v2
	v_add_u32_e32 v2, s8, v69
	s_and_b32 s9, s9, 0xff
	v_add_u32_e32 v2, v2, v148
	s_lshl_b32 s23, s9, 6
	v_pk_mul_f32 v[4:5], v[122:123], v[4:5]
	v_mad_u32_u24 v2, v2, s42, v153
	s_add_i32 s9, s23, s8
	ds_read_b128 v[10:13], v2
	v_cvt_pk_bf16_f32 v2, v4, v5
	v_cvt_pk_bf16_f32 v5, v18, v19
	v_add_u32_e32 v18, s9, v148
	s_add_i32 s9, s58, 0xfffe
	s_add_i32 s24, s23, s59
	s_and_b32 s20, s9, 0xff
	v_cvt_pk_bf16_f32 v3, v14, v15
	v_add_u32_e32 v14, s24, v148
	s_mulk_i32 s20, 0xab
	v_mad_i32_i24 v14, v14, s42, v153
	s_lshr_b32 s20, s20, 11
	v_cvt_pk_bf16_f32 v4, v16, v17
	ds_read_b128 v[14:17], v14
	s_mul_i32 s20, s20, 12
	s_sub_i32 s9, s9, s20
	s_waitcnt lgkmcnt(2)
	v_mfma_f32_16x16x32_bf16 v[6:9], v[6:9], v[2:5], 0
	s_and_b32 s9, s9, 0xff
	v_mad_u32_u24 v18, v18, s42, v153
	s_lshl_b32 s21, s9, 6
	ds_read_b128 v[18:21], v18
	s_add_i32 s9, s21, s8
	s_waitcnt lgkmcnt(2)
	v_mfma_f32_16x16x32_bf16 v[10:13], v[10:13], v[2:5], 0
	s_add_i32 s22, s21, s59
	v_add_u32_e32 v26, s9, v148
	s_add_i32 s9, s58, 0xffff
	v_lshlrev_b32_e32 v75, 16, v66
	v_add_u32_e32 v22, s22, v148
	s_and_b32 s20, s9, 0xff
	v_add_f32_e32 v75, v6, v75
	v_and_b32_e32 v6, 0xffff0000, v66
	v_lshlrev_b32_e32 v66, 16, v67
	v_mad_i32_i24 v22, v22, s42, v153
	s_mulk_i32 s20, 0xab
	v_add_f32_e32 v8, v8, v66
	v_and_b32_e32 v66, 0xffff0000, v67
	ds_read_b128 v[22:25], v22
	s_lshr_b32 s20, s20, 11
	v_add_f32_e32 v9, v9, v66
	v_lshlrev_b32_e32 v66, 16, v68
	s_waitcnt lgkmcnt(2)
	v_mfma_f32_16x16x32_bf16 v[14:17], v[14:17], v[2:5], 0
	s_mul_i32 s20, s20, 12
	v_add_f32_e32 v10, v10, v66
	v_and_b32_e32 v66, 0xffff0000, v68
	s_sub_i32 s9, s9, s20
	v_add_f32_e32 v11, v11, v66
	v_lshlrev_b32_e32 v66, 16, v37
	v_mad_u32_u24 v26, v26, s42, v153
	s_and_b32 s9, s9, 0xff
	v_add_f32_e32 v12, v12, v66
	v_and_b32_e32 v66, 0xffff0000, v37
	ds_read_b128 v[26:29], v26
	s_lshl_b32 s9, s9, 6
	v_add_f32_e32 v13, v13, v66
	v_lshlrev_b32_e32 v66, 16, v38
	s_waitcnt lgkmcnt(2)
	v_mfma_f32_16x16x32_bf16 v[18:21], v[18:21], v[2:5], 0
	s_add_i32 s20, s9, s59
	v_add_f32_e32 v66, v14, v66
	v_and_b32_e32 v14, 0xffff0000, v38
	v_add_u32_e32 v30, s20, v148
	v_add_f32_e32 v67, v15, v14
	v_lshlrev_b32_e32 v14, 16, v39
	v_mad_i32_i24 v30, v30, s42, v153
	v_add_f32_e32 v68, v16, v14
	v_and_b32_e32 v14, 0xffff0000, v39
	ds_read_b128 v[30:33], v30
	v_add_f32_e32 v76, v17, v14
	v_lshlrev_b32_e32 v14, 16, v40
	s_waitcnt lgkmcnt(2)
	v_mfma_f32_16x16x32_bf16 v[22:25], v[22:25], v[2:5], 0
	s_add_i32 s25, s9, s8
	v_add_f32_e32 v77, v18, v14
	v_and_b32_e32 v14, 0xffff0000, v40
	v_add_u32_e32 v70, s25, v148
	v_add_f32_e32 v78, v19, v14
	v_lshlrev_b32_e32 v14, 16, v41
	v_mad_u32_u24 v70, v70, s42, v153
	v_add_f32_e32 v79, v20, v14
	v_and_b32_e32 v14, 0xffff0000, v41
	ds_read_b128 v[70:73], v70
	v_add_f32_e32 v80, v21, v14
	v_lshlrev_b32_e32 v14, 16, v42
	s_waitcnt lgkmcnt(2)
	v_mfma_f32_16x16x32_bf16 v[26:29], v[26:29], v[2:5], 0
	v_add_f32_e32 v7, v7, v6
	v_add_f32_e32 v81, v22, v14
	v_and_b32_e32 v14, 0xffff0000, v42
	v_max3_f32 v6, v75, s44, v7
	v_add_f32_e32 v82, v23, v14
	v_lshlrev_b32_e32 v14, 16, v43
	v_max3_f32 v6, v6, v8, v9
	v_add_f32_e32 v83, v24, v14
	v_and_b32_e32 v14, 0xffff0000, v43
	v_max3_f32 v6, v6, v10, v11
	v_add_f32_e32 v84, v25, v14
	v_lshlrev_b32_e32 v14, 16, v44
	s_waitcnt lgkmcnt(1)
	v_mfma_f32_16x16x32_bf16 v[30:33], v[30:33], v[2:5], 0
	v_max3_f32 v6, v6, v12, v13
	v_add_f32_e32 v26, v26, v14
	v_and_b32_e32 v14, 0xffff0000, v44
	v_max3_f32 v6, v6, v66, v67
	v_add_f32_e32 v27, v27, v14
	v_lshlrev_b32_e32 v14, 16, v45
	v_max3_f32 v6, v6, v68, v76
	v_add_f32_e32 v28, v28, v14
	v_and_b32_e32 v14, 0xffff0000, v45
	v_max3_f32 v6, v6, v77, v78
	v_add_f32_e32 v29, v29, v14
	v_lshlrev_b32_e32 v14, 16, v46
	s_waitcnt lgkmcnt(0)
	v_mfma_f32_16x16x32_bf16 v[70:73], v[70:73], v[2:5], 0
	v_max3_f32 v6, v6, v79, v80
	v_add_f32_e32 v30, v30, v14
	v_and_b32_e32 v14, 0xffff0000, v46
	v_max3_f32 v6, v6, v81, v82
	v_add_f32_e32 v31, v31, v14
	v_lshlrev_b32_e32 v14, 16, v47
	v_max3_f32 v6, v6, v83, v84
	v_add_f32_e32 v32, v32, v14
	v_and_b32_e32 v14, 0xffff0000, v47
	v_max3_f32 v6, v6, v26, v27
	v_add_f32_e32 v33, v33, v14
	v_lshlrev_b32_e32 v14, 16, v48
	v_max3_f32 v6, v6, v28, v29
	v_add_f32_e32 v70, v70, v14
	v_and_b32_e32 v14, 0xffff0000, v48
	v_max3_f32 v6, v6, v30, v31
	v_add_f32_e32 v71, v71, v14
	v_lshlrev_b32_e32 v14, 16, v49
	v_max3_f32 v6, v6, v32, v33
	v_add_f32_e32 v72, v72, v14
	v_and_b32_e32 v14, 0xffff0000, v49
	v_max3_f32 v6, v6, v70, v71
	v_add_f32_e32 v73, v73, v14
	v_max3_f32 v6, v6, v72, v73
	v_mov_b32_e32 v14, v6
	s_nop 1
	v_permlane16_swap_b32_e32 v6, v14
	v_max_f32_e32 v14, v14, v14
	v_max_f32_e32 v6, v6, v6
	v_max_f32_e32 v6, v6, v14
	v_mov_b32_e32 v14, v6
	s_nop 1
	v_permlane32_swap_b32_e32 v6, v14
	v_max3_f32 v86, v6, v14, s44
	v_sub_f32_e32 v14, v75, v86
	v_sub_f32_e32 v7, v7, v86
	v_sub_f32_e32 v8, v8, v86
	v_sub_f32_e32 v9, v9, v86
	v_exp_f32_e32 v14, v14
	v_sub_f32_e32 v10, v10, v86
	v_exp_f32_e32 v7, v7
	v_exp_f32_e32 v8, v8
	v_exp_f32_e32 v9, v9
	v_exp_f32_e32 v15, v10
	v_sub_f32_e32 v10, v11, v86
	v_exp_f32_e32 v16, v10
	v_sub_f32_e32 v10, v12, v86
	v_exp_f32_e32 v75, v10
	v_sub_f32_e32 v10, v13, v86
	v_exp_f32_e32 v87, v10
	v_add_f32_e32 v10, v14, v7
	v_add_f32_e32 v11, v8, v9
	v_add_f32_e32 v88, v10, v11
	v_cvt_pk_bf16_f32 v11, v8, v9
	v_or_b32_e32 v8, s57, v69
	v_cvt_pk_bf16_f32 v10, v14, v7
	v_lshl_add_u32 v7, v74, 1, v157
	v_lshl_add_u32 v18, v8, 1, v157
	v_add_f32_e32 v89, v15, v16
	v_cvt_pk_bf16_f32 v12, v15, v16
	ds_read_b64 v[14:15], v7
	ds_read_b64 v[16:17], v18 offset:16
	v_add_u32_e32 v18, 0x8000, v18
	ds_read_b64 v[20:21], v18 offset:272
	ds_read_b64 v[18:19], v18 offset:240
	v_sub_f32_e32 v6, 0xff800000, v86
	v_exp_f32_e32 v85, v6
	v_cvt_pk_bf16_f32 v13, v75, v87
	s_or_b32 s23, s23, s57
	v_add_f32_e32 v74, v89, v88
	v_mul_f32_e32 v6, 0, v85
	v_mov_b32_e32 v7, v6
	v_mov_b32_e32 v8, v6
	v_mov_b32_e32 v9, v6
	v_add_f32_e32 v75, v75, v87
	v_lshl_add_u32 v69, s23, 1, v157
	s_waitcnt lgkmcnt(2)
	v_mfma_f32_16x16x32_bf16 v[14:17], v[14:17], v[10:13], v[6:9]
	v_add_f32_e32 v74, v75, v74
	v_lshl_add_u32 v22, s24, 1, v157
	ds_read_b64 v[22:23], v22
	ds_read_b64 v[24:25], v69 offset:16
	s_waitcnt lgkmcnt(2)
	v_mfma_f32_16x16x32_bf16 v[6:9], v[18:21], v[10:13], v[6:9]
	v_sub_f32_e32 v10, v66, v86
	v_exp_f32_e32 v18, v10
	v_sub_f32_e32 v10, v77, v86
	v_exp_f32_e32 v20, v10
	v_sub_f32_e32 v10, v67, v86
	v_exp_f32_e32 v19, v10
	v_sub_f32_e32 v10, v78, v86
	v_exp_f32_e32 v21, v10
	v_sub_f32_e32 v10, v68, v86
	v_exp_f32_e32 v66, v10
	v_sub_f32_e32 v10, v79, v86
	v_exp_f32_e32 v67, v10
	v_sub_f32_e32 v10, v76, v86
	v_exp_f32_e32 v68, v10
	v_sub_f32_e32 v10, v80, v86
	v_exp_f32_e32 v75, v10
	v_add_f32_e32 v10, v18, v19
	v_add_f32_e32 v11, v66, v68
	v_add_f32_e32 v76, v10, v11
	v_add_u32_e32 v10, 0x8000, v69
	ds_read_b64 v[12:13], v10 offset:272
	ds_read_b64 v[10:11], v10 offset:240
	v_add_f32_e32 v77, v20, v21
	v_cvt_pk_bf16_f32 v18, v18, v19
	v_cvt_pk_bf16_f32 v19, v66, v68
	v_cvt_pk_bf16_f32 v20, v20, v21
	v_cvt_pk_bf16_f32 v21, v67, v75
	v_fmac_f32_e32 v74, 0, v85
	s_or_b32 s21, s21, s57
	s_waitcnt lgkmcnt(2)
	v_mfma_f32_16x16x32_bf16 v[14:17], v[22:25], v[18:21], v[14:17]
	v_add_f32_e32 v22, v77, v76
	v_add_f32_e32 v23, v67, v75
	v_add_f32_e32 v22, v23, v22
	s_waitcnt lgkmcnt(0)
	v_mfma_f32_16x16x32_bf16 v[6:9], v[10:13], v[18:21], v[6:9]
	v_sub_f32_e32 v10, v81, v86
	v_exp_f32_e32 v66, v10
	v_sub_f32_e32 v10, v26, v86
	v_add_f32_e32 v74, v22, v74
	v_exp_f32_e32 v67, v10
	v_sub_f32_e32 v10, v82, v86
	v_lshl_add_u32 v13, s22, 1, v157
	v_lshl_add_u32 v22, s21, 1, v157
	v_exp_f32_e32 v68, v10
	v_sub_f32_e32 v10, v27, v86
	ds_read_b64 v[18:19], v13
	ds_read_b64 v[20:21], v22 offset:16
	v_add_u32_e32 v22, 0x8000, v22
	v_exp_f32_e32 v69, v10
	v_sub_f32_e32 v10, v83, v86
	ds_read_b64 v[24:25], v22 offset:272
	ds_read_b64 v[22:23], v22 offset:240
	v_exp_f32_e32 v75, v10
	v_sub_f32_e32 v10, v28, v86
	v_exp_f32_e32 v76, v10
	v_sub_f32_e32 v10, v84, v86
	v_exp_f32_e32 v77, v10
	v_sub_f32_e32 v10, v29, v86
	v_exp_f32_e32 v78, v10
	v_cvt_pk_bf16_f32 v10, v66, v68
	v_cvt_pk_bf16_f32 v11, v75, v77
	v_cvt_pk_bf16_f32 v12, v67, v69
	v_cvt_pk_bf16_f32 v13, v76, v78
	s_or_b32 s9, s9, s57
	v_lshl_add_u32 v79, s9, 1, v157
	s_waitcnt lgkmcnt(2)
	v_mfma_f32_16x16x32_bf16 v[14:17], v[18:21], v[10:13], v[14:17]
	v_add_f32_e32 v19, v75, v77
	s_mul_i32 s9, s58, 0xab
	s_bfe_u32 s9, s9, 0x5000b
	s_waitcnt lgkmcnt(0)
	v_mfma_f32_16x16x32_bf16 v[6:9], v[22:25], v[10:13], v[6:9]
	v_sub_f32_e32 v10, v30, v86
	v_exp_f32_e32 v75, v10
	v_sub_f32_e32 v10, v70, v86
	v_exp_f32_e32 v87, v10
	v_sub_f32_e32 v10, v31, v86
	v_exp_f32_e32 v77, v10
	v_sub_f32_e32 v10, v71, v86
	v_exp_f32_e32 v88, v10
	v_sub_f32_e32 v10, v32, v86
	v_exp_f32_e32 v89, v10
	v_sub_f32_e32 v10, v72, v86
	s_mul_i32 s9, s9, 12
	v_exp_f32_e32 v90, v10
	v_sub_f32_e32 v10, v33, v86
	s_sub_i32 s9, s58, s9
	v_lshl_add_u32 v26, s20, 1, v157
	v_exp_f32_e32 v91, v10
	v_sub_f32_e32 v10, v73, v86
	s_and_b32 s9, s9, 0xff
	ds_read_b64 v[26:27], v26
	ds_read_b64 v[28:29], v79 offset:16
	v_exp_f32_e32 v92, v10
	s_lshl_b32 s25, s9, 6
	v_add_f32_e32 v18, v66, v68
	v_add_u32_e32 v11, 0x8000, v79
	s_add_i32 s26, s25, s59
	v_add_f32_e32 v66, v18, v19
	ds_read_b64 v[18:19], v11 offset:240
	ds_read_b64 v[20:21], v11 offset:272
	v_add_u32_e32 v11, s26, v148
	v_mad_i32_i24 v11, v11, s42, v153
	v_cvt_pk_bf16_f32 v10, v75, v77
	ds_read_b128 v[22:25], v11
	v_cvt_pk_bf16_f32 v11, v89, v91
	v_cvt_pk_bf16_f32 v12, v87, v88
	v_cvt_pk_bf16_f32 v13, v90, v92
	s_add_i32 s9, s25, s8
	v_add_f32_e32 v67, v67, v69
	s_waitcnt lgkmcnt(3)
	v_mfma_f32_16x16x32_bf16 v[26:29], v[26:29], v[10:13], v[14:17]
	v_add_f32_e32 v79, v67, v66
	v_add_f32_e32 v94, v75, v77
	v_add_f32_e32 v89, v89, v91
	v_add_u32_e32 v14, s9, v148
	s_add_i32 s9, s58, 1
	s_and_b32 s20, s9, 0xff
	s_mulk_i32 s20, 0xab
	s_lshr_b32 s20, s20, 11
	s_mul_i32 s20, s20, 12
	s_sub_i32 s9, s9, s20
	v_mad_u32_u24 v14, v14, s42, v153
	s_and_b32 s9, s9, 0xff
	ds_read_b128 v[14:17], v14
	s_lshl_b32 s23, s9, 6
	s_add_i32 s9, s23, s8
	s_add_i32 s24, s23, s59
	v_add_u32_e32 v66, s9, v148
	s_add_i32 s9, s58, 2
	v_add_u32_e32 v30, s24, v148
	s_and_b32 s20, s9, 0xff
	v_mad_i32_i24 v30, v30, s42, v153
	s_mulk_i32 s20, 0xab
	ds_read_b128 v[30:33], v30
	s_lshr_b32 s20, s20, 11
	s_mul_i32 s20, s20, 12
	s_waitcnt lgkmcnt(2)
	v_mfma_f32_16x16x32_bf16 v[22:25], v[22:25], v[2:5], 0
	s_sub_i32 s9, s9, s20
	v_mad_u32_u24 v66, v66, s42, v153
	s_and_b32 s9, s9, 0xff
	v_add_f32_e32 v89, v94, v89
	v_add_f32_e32 v87, v87, v88
	v_add_f32_e32 v76, v76, v78
	s_waitcnt lgkmcnt(1)
	v_mfma_f32_16x16x32_bf16 v[14:17], v[14:17], v[2:5], 0
	ds_read_b128 v[66:69], v66
	s_lshl_b32 s21, s9, 6
	v_add_f32_e32 v87, v87, v89
	v_add_f32_e32 v88, v90, v92
	s_add_i32 s22, s21, s59
	v_add_f32_e32 v76, v76, v79
	s_add_i32 s9, s21, s8
	s_add_i32 s58, s58, 3
	v_add_f32_e32 v87, v88, v87
	v_lshlrev_b32_e32 v88, 16, v50
	v_lshlrev_b32_e32 v89, 16, v51
	v_add_u32_e32 v70, s22, v148
	v_add_f32_e32 v93, v76, v74
	v_add_u32_e32 v74, s9, v148
	s_and_b32 s9, s58, 0xff
	v_add_f32_e32 v22, v22, v88
	v_and_b32_e32 v88, 0xffff0000, v50
	v_add_f32_e32 v24, v24, v89
	v_and_b32_e32 v89, 0xffff0000, v51
	v_mad_i32_i24 v70, v70, s42, v153
	s_mulk_i32 s9, 0xab
	v_add_f32_e32 v23, v23, v88
	v_add_f32_e32 v25, v25, v89
	v_lshlrev_b32_e32 v89, 16, v52
	ds_read_b128 v[70:73], v70
	s_lshr_b32 s9, s9, 11
	v_max3_f32 v88, v22, s44, v23
	v_add_f32_e32 v89, v14, v89
	v_and_b32_e32 v14, 0xffff0000, v52
	s_waitcnt lgkmcnt(2)
	v_mfma_f32_16x16x32_bf16 v[30:33], v[30:33], v[2:5], 0
	s_mul_i32 s9, s9, 12
	v_max3_f32 v88, v88, v24, v25
	v_add_f32_e32 v15, v15, v14
	s_sub_i32 s9, s58, s9
	v_max3_f32 v14, v88, v89, v15
	v_lshlrev_b32_e32 v88, 16, v53
	v_mad_u32_u24 v74, v74, s42, v153
	s_and_b32 s9, s9, 0xff
	v_add_f32_e32 v16, v16, v88
	v_and_b32_e32 v88, 0xffff0000, v53
	ds_read_b128 v[74:77], v74
	s_lshl_b32 s9, s9, 6
	v_add_f32_e32 v17, v17, v88
	v_lshlrev_b32_e32 v88, 16, v54
	s_waitcnt lgkmcnt(2)
	v_mfma_f32_16x16x32_bf16 v[66:69], v[66:69], v[2:5], 0
	s_add_i32 s20, s9, s59
	v_add_f32_e32 v88, v30, v88
	v_and_b32_e32 v30, 0xffff0000, v54
	v_add_u32_e32 v78, s20, v148
	v_add_f32_e32 v90, v31, v30
	v_lshlrev_b32_e32 v30, 16, v55
	v_mad_i32_i24 v78, v78, s42, v153
	v_add_f32_e32 v91, v32, v30
	v_and_b32_e32 v30, 0xffff0000, v55
	ds_read_b128 v[78:81], v78
	v_add_f32_e32 v33, v33, v30
	v_lshlrev_b32_e32 v30, 16, v56
	s_waitcnt lgkmcnt(2)
	v_mfma_f32_16x16x32_bf16 v[70:73], v[70:73], v[2:5], 0
	s_add_i32 s8, s9, s8
	v_add_f32_e32 v66, v66, v30
	v_and_b32_e32 v30, 0xffff0000, v56
	v_add_u32_e32 v82, s8, v148
	v_add_f32_e32 v67, v67, v30
	v_lshlrev_b32_e32 v30, 16, v57
	v_mad_u32_u24 v82, v82, s42, v153
	v_add_f32_e32 v68, v68, v30
	v_and_b32_e32 v30, 0xffff0000, v57
	ds_read_b128 v[82:85], v82
	v_add_f32_e32 v69, v69, v30
	v_lshlrev_b32_e32 v30, 16, v58
	s_waitcnt lgkmcnt(2)
	v_mfma_f32_16x16x32_bf16 v[74:77], v[74:77], v[2:5], 0
	v_add_f32_e32 v70, v70, v30
	v_and_b32_e32 v30, 0xffff0000, v58
	v_add_f32_e32 v71, v71, v30
	v_lshlrev_b32_e32 v30, 16, v59
	v_add_f32_e32 v72, v72, v30
	v_and_b32_e32 v30, 0xffff0000, v59
	v_add_f32_e32 v73, v73, v30
	v_lshlrev_b32_e32 v30, 16, v60
	s_waitcnt lgkmcnt(1)
	v_mfma_f32_16x16x32_bf16 v[78:81], v[78:81], v[2:5], 0
	v_max3_f32 v14, v14, v16, v17
	v_add_f32_e32 v74, v74, v30
	v_and_b32_e32 v30, 0xffff0000, v60
	v_max3_f32 v14, v14, v88, v90
	v_add_f32_e32 v75, v75, v30
	v_lshlrev_b32_e32 v30, 16, v61
	v_max3_f32 v14, v14, v91, v33
	v_add_f32_e32 v76, v76, v30
	v_and_b32_e32 v30, 0xffff0000, v61
	v_max3_f32 v14, v14, v66, v67
	v_add_f32_e32 v77, v77, v30
	v_lshlrev_b32_e32 v30, 16, v62
	s_waitcnt lgkmcnt(0)
	v_mfma_f32_16x16x32_bf16 v[82:85], v[82:85], v[2:5], 0
	v_max3_f32 v14, v14, v68, v69
	v_add_f32_e32 v78, v78, v30
	v_and_b32_e32 v30, 0xffff0000, v62
	v_max3_f32 v14, v14, v70, v71
	v_add_f32_e32 v79, v79, v30
	v_lshlrev_b32_e32 v30, 16, v63
	v_max3_f32 v14, v14, v72, v73
	v_add_f32_e32 v80, v80, v30
	v_and_b32_e32 v30, 0xffff0000, v63
	v_max3_f32 v14, v14, v74, v75
	v_add_f32_e32 v81, v81, v30
	v_lshlrev_b32_e32 v30, 16, v64
	v_max3_f32 v14, v14, v76, v77
	v_add_f32_e32 v82, v82, v30
	v_and_b32_e32 v30, 0xffff0000, v64
	v_max3_f32 v14, v14, v78, v79
	v_add_f32_e32 v83, v83, v30
	v_lshlrev_b32_e32 v30, 16, v65
	v_max3_f32 v14, v14, v80, v81
	v_add_f32_e32 v84, v84, v30
	v_and_b32_e32 v30, 0xffff0000, v65
	v_max3_f32 v14, v14, v82, v83
	v_add_f32_e32 v85, v85, v30
	v_max3_f32 v14, v14, v84, v85
	v_mov_b32_e32 v30, v14
	s_nop 1
	v_permlane16_swap_b32_e32 v14, v30
	v_max_f32_e32 v30, v30, v30
	v_max_f32_e32 v14, v14, v14
	v_max_f32_e32 v14, v14, v30
	v_mov_b32_e32 v30, v14
	s_nop 1
	v_permlane32_swap_b32_e32 v14, v30
	v_max3_f32 v14, v86, v14, v30
	v_sub_f32_e32 v16, v16, v14
	v_sub_f32_e32 v30, v86, v14
	v_mfma_f32_16x16x32_bf16 v[6:9], v[18:21], v[10:13], v[6:9]
	v_add_f32_e32 v86, v87, v93
	v_sub_f32_e32 v18, v22, v14
	v_sub_f32_e32 v20, v23, v14
	v_sub_f32_e32 v21, v24, v14
	v_exp_f32_e32 v87, v16
	v_sub_f32_e32 v16, v25, v14
	v_exp_f32_e32 v18, v18
	v_sub_f32_e32 v19, v89, v14
	v_exp_f32_e32 v20, v20
	v_sub_f32_e32 v15, v15, v14
	v_exp_f32_e32 v21, v21
	v_exp_f32_e32 v22, v16
	v_exp_f32_e32 v19, v19
	v_exp_f32_e32 v15, v15
	v_exp_f32_e32 v32, v30
	v_sub_f32_e32 v16, v17, v14
	v_exp_f32_e32 v89, v16
	v_add_f32_e32 v16, v18, v20
	v_add_f32_e32 v17, v21, v22
	s_or_b32 s25, s25, s57
	v_add_f32_e32 v92, v16, v17
	v_add_f32_e32 v93, v19, v15
	v_cvt_pk_bf16_f32 v16, v18, v20
	v_cvt_pk_bf16_f32 v18, v19, v15
	v_lshl_add_u32 v15, s26, 1, v157
	v_lshl_add_u32 v24, s25, 1, v157
	v_cvt_pk_bf16_f32 v17, v21, v22
	ds_read_b64 v[20:21], v15
	ds_read_b64 v[22:23], v24 offset:16
	v_add_u32_e32 v15, 0x8000, v24
	v_pk_mul_f32 v[10:11], v[26:27], v[32:33] op_sel_hi:[1,0]
	ds_read_b64 v[24:25], v15 offset:240
	ds_read_b64 v[26:27], v15 offset:272
	v_pk_mul_f32 v[12:13], v[28:29], v[32:33] op_sel_hi:[1,0]
	v_pk_mul_f32 v[8:9], v[8:9], v[32:33] op_sel_hi:[1,0]
	v_pk_mul_f32 v[6:7], v[6:7], v[32:33] op_sel_hi:[1,0]
	v_cvt_pk_bf16_f32 v19, v87, v89
	v_lshl_add_u32 v15, s24, 1, v157
	s_or_b32 s23, s23, s57
	v_lshl_add_u32 v94, s23, 1, v157
	ds_read_b64 v[28:29], v15
	ds_read_b64 v[30:31], v94 offset:16
	s_waitcnt lgkmcnt(4)
	v_mfma_f32_16x16x32_bf16 v[10:13], v[20:23], v[16:19], v[10:13]
	v_add_f32_e32 v15, v93, v92
	v_add_f32_e32 v20, v87, v89
	v_add_f32_e32 v15, v20, v15
	s_waitcnt lgkmcnt(2)
	v_mfma_f32_16x16x32_bf16 v[6:9], v[24:27], v[16:19], v[6:9]
	v_sub_f32_e32 v16, v88, v14
	v_exp_f32_e32 v20, v16
	v_sub_f32_e32 v16, v66, v14
	v_exp_f32_e32 v22, v16
	v_sub_f32_e32 v16, v90, v14
	v_exp_f32_e32 v21, v16
	v_sub_f32_e32 v16, v67, v14
	v_exp_f32_e32 v23, v16
	v_sub_f32_e32 v16, v91, v14
	v_exp_f32_e32 v24, v16
	v_sub_f32_e32 v16, v68, v14
	v_exp_f32_e32 v25, v16
	v_sub_f32_e32 v16, v33, v14
	v_exp_f32_e32 v26, v16
	v_sub_f32_e32 v16, v69, v14
	v_exp_f32_e32 v27, v16
	v_add_f32_e32 v16, v20, v21
	v_add_f32_e32 v17, v24, v26
	v_fmac_f32_e32 v15, v86, v32
	v_add_f32_e32 v32, v16, v17
	v_add_u32_e32 v16, 0x8000, v94
	ds_read_b64 v[18:19], v16 offset:272
	ds_read_b64 v[16:17], v16 offset:240
	v_add_f32_e32 v33, v22, v23
	v_cvt_pk_bf16_f32 v20, v20, v21
	v_cvt_pk_bf16_f32 v21, v24, v26
	v_cvt_pk_bf16_f32 v22, v22, v23
	v_cvt_pk_bf16_f32 v23, v25, v27
	v_add_f32_e32 v24, v33, v32
	v_add_f32_e32 v25, v25, v27
	s_waitcnt lgkmcnt(2)
	v_mfma_f32_16x16x32_bf16 v[10:13], v[28:31], v[20:23], v[10:13]
	v_add_f32_e32 v24, v25, v24
	s_or_b32 s21, s21, s57
	v_add_f32_e32 v15, v24, v15
	s_waitcnt lgkmcnt(0)
	v_mfma_f32_16x16x32_bf16 v[6:9], v[16:19], v[20:23], v[6:9]
	v_sub_f32_e32 v17, v74, v14
	v_sub_f32_e32 v21, v76, v14
	v_sub_f32_e32 v16, v70, v14
	v_exp_f32_e32 v18, v17
	v_sub_f32_e32 v17, v71, v14
	v_sub_f32_e32 v19, v75, v14
	v_sub_f32_e32 v20, v72, v14
	v_exp_f32_e32 v32, v21
	v_sub_f32_e32 v21, v73, v14
	v_exp_f32_e32 v16, v16
	v_exp_f32_e32 v17, v17
	v_exp_f32_e32 v19, v19
	v_exp_f32_e32 v20, v20
	v_exp_f32_e32 v21, v21
	v_sub_f32_e32 v22, v77, v14
	v_exp_f32_e32 v33, v22
	v_add_f32_e32 v22, v16, v17
	v_add_f32_e32 v23, v20, v21
	v_add_f32_e32 v67, v18, v19
	v_cvt_pk_bf16_f32 v18, v18, v19
	v_lshl_add_u32 v19, s22, 1, v157
	v_lshl_add_u32 v24, s21, 1, v157
	v_add_f32_e32 v66, v22, v23
	v_cvt_pk_bf16_f32 v16, v16, v17
	v_cvt_pk_bf16_f32 v17, v20, v21
	ds_read_b64 v[20:21], v19
	ds_read_b64 v[22:23], v24 offset:16
	v_add_u32_e32 v24, 0x8000, v24
	ds_read_b64 v[26:27], v24 offset:272
	ds_read_b64 v[24:25], v24 offset:240
	v_cvt_pk_bf16_f32 v19, v32, v33
	s_or_b32 s9, s9, s57
	v_lshl_add_u32 v68, s9, 1, v157
	s_waitcnt lgkmcnt(2)
	v_mfma_f32_16x16x32_bf16 v[10:13], v[20:23], v[16:19], v[10:13]
	v_add_f32_e32 v20, v67, v66
	v_add_f32_e32 v21, v32, v33
	v_add_f32_e32 v20, v21, v20
	v_add_f32_e32 v15, v20, v15
	v_sub_f32_e32 v20, v80, v14
	s_waitcnt lgkmcnt(0)
	v_mfma_f32_16x16x32_bf16 v[16:19], v[24:27], v[16:19], v[6:9]
	v_exp_f32_e32 v25, v20
	v_sub_f32_e32 v20, v84, v14
	v_exp_f32_e32 v32, v20
	v_sub_f32_e32 v6, v78, v14
	v_sub_f32_e32 v8, v79, v14
	v_sub_f32_e32 v20, v81, v14
	v_exp_f32_e32 v6, v6
	v_exp_f32_e32 v8, v8
	v_exp_f32_e32 v26, v20
	v_sub_f32_e32 v20, v85, v14
	v_exp_f32_e32 v33, v20
	v_add_f32_e32 v20, v6, v8
	v_add_f32_e32 v21, v25, v26
	v_lshl_add_u32 v28, s20, 1, v157
	v_add_f32_e32 v66, v20, v21
	v_add_u32_e32 v20, 0x8000, v68
	ds_read_b64 v[28:29], v28
	ds_read_b64 v[30:31], v68 offset:16
	ds_read_b64 v[22:23], v20 offset:272
	ds_read_b64 v[20:21], v20 offset:240
	v_sub_f32_e32 v7, v82, v14
	v_sub_f32_e32 v9, v83, v14
	v_exp_f32_e32 v7, v7
	v_exp_f32_e32 v9, v9
	v_cvt_pk_bf16_f32 v24, v6, v8
	v_cvt_pk_bf16_f32 v25, v25, v26
	v_cvt_pk_bf16_f32 v27, v32, v33
	v_add_f32_e32 v67, v7, v9
	v_cvt_pk_bf16_f32 v26, v7, v9
	s_mov_b32 s8, 2
	s_waitcnt lgkmcnt(2)
	v_mfma_f32_16x16x32_bf16 v[6:9], v[28:31], v[24:27], v[10:13]
	s_nop 2
	v_add_f32_e32 v10, v67, v66
	v_add_f32_e32 v11, v32, v33
	v_add_f32_e32 v28, v11, v10
	s_waitcnt lgkmcnt(0)
	v_mfma_f32_16x16x32_bf16 v[10:13], v[20:23], v[24:27], v[16:19]
	s_nop 2
	v_add_f32_e32 v17, v28, v15
	v_mov_b32_e32 v15, v150
	v_mov_b32_e32 v16, v156

.LBB0_2373:
	v_cmp_le_i32_e32 vcc, v87, v91
	s_waitcnt lgkmcnt(2)
	v_pk_mul_f32 v[20:21], v[52:53], v[20:21]
	v_mul_lo_u32 v52, v183, s13
	s_nop 1
	v_cndmask_b32_e32 v48, 0, v48, vcc
	v_cmp_lt_i32_e32 vcc, v87, v91
	v_lshlrev_b32_e32 v53, 1, v86
	v_pk_mul_f32 v[44:45], v[72:73], v[44:45]
	v_cndmask_b32_e32 v49, 0, v49, vcc
	v_cmp_le_i32_e32 vcc, v88, v91
	v_cvt_pk_bf16_f32 v48, v48, v49
	v_add3_u32 v72, 0, v52, v53
	v_cndmask_b32_e32 v50, 0, v50, vcc
	v_cmp_le_i32_e32 vcc, v89, v91
	v_pk_mul_f32 v[22:23], v[54:55], v[22:23]
	v_pk_mul_f32 v[46:47], v[74:75], v[46:47]
	v_cndmask_b32_e32 v51, 0, v51, vcc
	v_cvt_pk_bf16_f32 v49, v50, v51
	v_mul_lo_u32 v50, v91, s14
	v_add3_u32 v50, s15, v50, v90
	ds_write_b64 v50, v[48:49]
	ds_read_b64 v[52:53], v72
	ds_read_b64 v[54:55], v72 offset:32
	v_add_u32_e32 v73, 0x1000, v72
	v_add_u32_e32 v74, 0x2000, v72
	v_add_u32_e32 v75, 0x3000, v72
	v_pk_mul_f32 v[34:35], v[66:67], v[34:35]
	v_pk_mul_f32 v[32:33], v[64:65], v[32:33]
	v_pk_mul_f32 v[30:31], v[62:63], v[30:31]
	v_pk_mul_f32 v[28:29], v[60:61], v[28:29]
	v_pk_mul_f32 v[26:27], v[58:59], v[26:27]
	v_pk_mul_f32 v[24:25], v[56:57], v[24:25]
	ds_read_b64 v[56:57], v73 offset:512
	ds_read_b64 v[58:59], v73 offset:544
	ds_read_b64 v[60:61], v74 offset:1024
	ds_read_b64 v[62:63], v74 offset:1056
	ds_read_b64 v[64:65], v75 offset:1536
	ds_read_b64 v[66:67], v75 offset:1568
	v_pk_mul_f32 v[38:39], v[70:71], v[38:39]
	v_pk_mul_f32 v[36:37], v[68:69], v[36:37]
	ds_read_b64 v[68:69], v72 offset:64
	ds_read_b64 v[70:71], v72 offset:96
	v_pk_mul_f32 v[42:43], v[78:79], v[42:43]
	v_pk_mul_f32 v[40:41], v[76:77], v[40:41]
	v_cvt_pk_bf16_f32 v49, v42, v43
	v_cvt_pk_bf16_f32 v48, v40, v41
	v_cvt_pk_bf16_f32 v50, v44, v45
	v_cvt_pk_bf16_f32 v51, v46, v47
	s_waitcnt lgkmcnt(12)
	v_pk_mul_f32 v[18:19], v[82:83], v[18:19]
	v_pk_mul_f32 v[16:17], v[80:81], v[16:17]
	s_waitcnt lgkmcnt(8)
	v_mfma_f32_16x16x32_bf16 v[52:55], v[52:55], v[48:51], 0
	v_lshlrev_b32_e32 v85, 3, v102
	v_mul_lo_u32 v76, v183, s14
	v_add_u32_e32 v80, 0xa00, v76
	s_waitcnt lgkmcnt(6)
	v_mfma_f32_16x16x32_bf16 v[56:59], v[56:59], v[48:51], 0
	v_add_u32_e32 v87, 0x1400, v76
	v_add_u32_e32 v88, 0x1e00, v76
	v_add_u32_e32 v99, v84, v76
	s_waitcnt lgkmcnt(4)
	v_mfma_f32_16x16x32_bf16 v[60:63], v[60:63], v[48:51], 0
	v_add_u32_e32 v118, v84, v80
	v_add_u32_e32 v119, v84, v87
	v_add_u32_e32 v120, v84, v88
	s_waitcnt lgkmcnt(2)
	v_mfma_f32_16x16x32_bf16 v[48:51], v[64:67], v[48:51], 0
	v_cvt_pk_bf16_f32 v64, v36, v37
	v_cvt_pk_bf16_f32 v65, v38, v39
	v_cvt_pk_bf16_f32 v66, v32, v33
	v_cvt_pk_bf16_f32 v67, v34, v35
	s_movk_i32 s8, 0x840
	s_and_b64 vcc, exec, s[0:1]
	s_waitcnt lgkmcnt(0)
	v_mfma_f32_16x16x32_bf16 v[52:55], v[68:71], v[64:67], v[52:55]
	ds_read_b64 v[68:69], v73 offset:576
	ds_read_b64 v[70:71], v73 offset:608
	s_waitcnt lgkmcnt(0)
	v_mfma_f32_16x16x32_bf16 v[56:59], v[68:71], v[64:67], v[56:59]
	ds_read_b64 v[68:69], v74 offset:1088
	ds_read_b64 v[70:71], v74 offset:1120
	s_waitcnt lgkmcnt(0)
	v_mfma_f32_16x16x32_bf16 v[60:63], v[68:71], v[64:67], v[60:63]
	ds_read_b64 v[68:69], v75 offset:1600
	ds_read_b64 v[70:71], v75 offset:1632
	s_waitcnt lgkmcnt(0)
	v_mfma_f32_16x16x32_bf16 v[48:51], v[68:71], v[64:67], v[48:51]
	ds_read_b64 v[68:69], v72 offset:128
	ds_read_b64 v[70:71], v72 offset:160
	v_cvt_pk_bf16_f32 v64, v28, v29
	v_cvt_pk_bf16_f32 v65, v30, v31
	v_cvt_pk_bf16_f32 v66, v24, v25
	v_cvt_pk_bf16_f32 v67, v26, v27
	s_waitcnt lgkmcnt(0)
	s_nop 0
	v_mfma_f32_16x16x32_bf16 v[52:55], v[68:71], v[64:67], v[52:55]
	ds_read_b64 v[68:69], v73 offset:640
	ds_read_b64 v[70:71], v73 offset:672
	s_waitcnt lgkmcnt(0)
	v_mfma_f32_16x16x32_bf16 v[56:59], v[68:71], v[64:67], v[56:59]
	ds_read_b64 v[68:69], v74 offset:1152
	ds_read_b64 v[70:71], v74 offset:1184
	s_waitcnt lgkmcnt(0)
	v_mfma_f32_16x16x32_bf16 v[60:63], v[68:71], v[64:67], v[60:63]
	ds_read_b64 v[68:69], v75 offset:1664
	ds_read_b64 v[70:71], v75 offset:1696
	s_waitcnt lgkmcnt(0)
	v_mfma_f32_16x16x32_bf16 v[48:51], v[68:71], v[64:67], v[48:51]
	ds_read_b64 v[68:69], v72 offset:192
	ds_read_b64 v[70:71], v72 offset:224
	v_cvt_pk_bf16_f32 v64, v20, v21
	v_cvt_pk_bf16_f32 v65, v22, v23
	v_cvt_pk_bf16_f32 v66, v16, v17
	v_cvt_pk_bf16_f32 v67, v18, v19
	s_waitcnt lgkmcnt(0)
	s_nop 0
	v_mfma_f32_16x16x32_bf16 v[52:55], v[68:71], v[64:67], v[52:55]
	ds_read_b64 v[68:69], v73 offset:704
	ds_read_b64 v[70:71], v73 offset:736
	s_waitcnt lgkmcnt(0)
	v_mfma_f32_16x16x32_bf16 v[56:59], v[68:71], v[64:67], v[56:59]
	ds_read_b64 v[68:69], v74 offset:1216
	ds_read_b64 v[70:71], v74 offset:1248
	s_waitcnt lgkmcnt(0)
	v_mfma_f32_16x16x32_bf16 v[60:63], v[68:71], v[64:67], v[60:63]
	ds_read_b64 v[68:69], v75 offset:1728
	ds_read_b64 v[70:71], v75 offset:1760
	s_waitcnt lgkmcnt(0)
	s_barrier
	s_waitcnt lgkmcnt(0)
	v_mfma_f32_16x16x32_bf16 v[48:51], v[68:71], v[64:67], v[48:51]
	v_add_u32_e32 v64, s34, v183
	v_lshlrev_b32_e32 v65, 1, v85
	v_mul_lo_u32 v64, v64, s14
	v_add_u32_e32 v72, s15, v65
	v_add3_u32 v85, 0, v64, v65
	v_add_u32_e32 v86, v72, v76
	v_add_u32_e32 v90, v72, v80
	v_add_u32_e32 v94, v72, v87
	v_add_u32_e32 v98, v72, v88
	ds_read_b128 v[240:243], v85 offset:57344
	ds_read_b128 v[208:211], v86
	ds_read_b128 v[212:215], v90
	ds_read_b128 v[216:219], v94
	ds_read_b128 v[220:223], v98
	ds_read_b128 v[224:227], v99 offset:36864
	ds_read_b128 v[228:231], v118 offset:36864
	ds_read_b128 v[232:235], v119 offset:36864
	ds_read_b128 v[236:239], v120 offset:36864
	s_waitcnt lgkmcnt(7)
	v_mfma_f32_16x16x32_bf16 v[68:71], v[208:211], v[240:243], v[52:55]
	ds_read_b128 v[208:211], v99 offset:47104
	s_waitcnt lgkmcnt(7)
	v_mfma_f32_16x16x32_bf16 v[56:59], v[212:215], v[240:243], v[56:59]
	ds_read_b128 v[212:215], v99 offset:49664
	s_waitcnt lgkmcnt(7)
	v_mfma_f32_16x16x32_bf16 v[60:63], v[216:219], v[240:243], v[60:63]
	ds_read_b128 v[216:219], v99 offset:52224
	s_waitcnt lgkmcnt(7)
	v_mfma_f32_16x16x32_bf16 v[72:75], v[220:223], v[240:243], v[48:51]
	ds_read_b128 v[220:223], v99 offset:54784
	s_waitcnt lgkmcnt(7)
	v_mfma_f32_16x16x32_bf16 v[76:79], v[224:227], v[240:243], v[40:43]
	ds_read_b128 v[244:247], v85 offset:57408
	ds_read_b128 v[224:227], v86 offset:64
	s_waitcnt lgkmcnt(8)
	v_mfma_f32_16x16x32_bf16 v[80:83], v[228:231], v[240:243], v[44:47]
	ds_read_b128 v[228:231], v120 offset:36928
	s_waitcnt lgkmcnt(8)
	v_mfma_f32_16x16x32_bf16 v[52:55], v[232:235], v[240:243], v[36:39]
	ds_read_b128 v[232:235], v90 offset:64
	s_waitcnt lgkmcnt(8)
	v_mfma_f32_16x16x32_bf16 v[48:51], v[236:239], v[240:243], v[32:35]
	ds_read_b128 v[236:239], v99 offset:47168
	s_waitcnt lgkmcnt(8)
	v_mfma_f32_16x16x32_bf16 v[32:35], v[208:211], v[240:243], v[28:31]
	ds_read_b128 v[208:211], v94 offset:64
	s_waitcnt lgkmcnt(8)
	v_mfma_f32_16x16x32_bf16 v[36:39], v[212:215], v[240:243], v[24:27]
	ds_read_b128 v[212:215], v99 offset:49728
	s_waitcnt lgkmcnt(8)
	v_mfma_f32_16x16x32_bf16 v[40:43], v[216:219], v[240:243], v[20:23]
	ds_read_b128 v[216:219], v98 offset:64
	s_waitcnt lgkmcnt(8)
	v_mfma_f32_16x16x32_bf16 v[44:47], v[220:223], v[240:243], v[16:19]
	ds_read_b128 v[220:223], v99 offset:52288
	s_waitcnt lgkmcnt(7)
	v_mfma_f32_16x16x32_bf16 v[86:89], v[224:227], v[244:247], v[68:71]
	ds_read_b128 v[224:227], v118 offset:36928
	s_waitcnt lgkmcnt(7)
	v_mfma_f32_16x16x32_bf16 v[28:31], v[228:231], v[244:247], v[48:51]
	ds_read_b128 v[228:231], v99 offset:54848
	s_waitcnt lgkmcnt(7)
	v_mfma_f32_16x16x32_bf16 v[90:93], v[232:235], v[244:247], v[56:59]
	ds_read_b128 v[232:235], v99 offset:36928
	s_waitcnt lgkmcnt(7)
	v_mfma_f32_16x16x32_bf16 v[32:35], v[236:239], v[244:247], v[32:35]
	ds_read_b128 v[236:239], v119 offset:36928
	s_waitcnt lgkmcnt(7)
	v_mfma_f32_16x16x32_bf16 v[94:97], v[208:211], v[244:247], v[60:63]
	s_waitcnt lgkmcnt(6)
	v_mfma_f32_16x16x32_bf16 v[36:39], v[212:215], v[244:247], v[36:39]
	s_waitcnt lgkmcnt(5)
	v_mfma_f32_16x16x32_bf16 v[114:117], v[216:219], v[244:247], v[72:75]
	s_waitcnt lgkmcnt(4)
	v_mfma_f32_16x16x32_bf16 v[40:43], v[220:223], v[244:247], v[40:43]
	s_waitcnt lgkmcnt(3)
	v_mfma_f32_16x16x32_bf16 v[20:23], v[224:227], v[244:247], v[80:83]
	s_waitcnt lgkmcnt(2)
	v_mfma_f32_16x16x32_bf16 v[44:47], v[228:231], v[244:247], v[44:47]
	s_waitcnt lgkmcnt(1)
	v_mfma_f32_16x16x32_bf16 v[16:19], v[232:235], v[244:247], v[76:79]
	s_waitcnt lgkmcnt(0)
	v_mfma_f32_16x16x32_bf16 v[24:27], v[236:239], v[244:247], v[52:55]
	v_lshlrev_b32_e32 v80, 2, v183
	v_mul_lo_u32 v81, v102, s8
	v_add3_u32 v80, s72, v80, v81
	v_add_u32_e32 v48, 0x1ea00, v84
	v_add_u32_e32 v81, 0x400, v80
	s_movk_i32 s8, 0x210
	s_nop 1
	ds_read_b128 v[76:79], v48
	ds_read_b128 v[72:75], v48 offset:64
	ds_read_b128 v[68:71], v48 offset:128
	ds_read_b128 v[64:67], v48 offset:192
	ds_read_b128 v[60:63], v48 offset:256
	ds_read_b128 v[56:59], v48 offset:320
	ds_read_b128 v[52:55], v48 offset:384
	ds_read_b128 v[48:51], v48 offset:448
	ds_write2_b32 v81, v88, v89 offset0:8 offset1:140
	v_add_u32_e32 v81, 0x2000, v80
	ds_write2_b32 v81, v90, v91 offset0:64 offset1:196
	v_add_u32_e32 v81, 0x2400, v80
	ds_write2_b32 v81, v92, v93 offset0:72 offset1:204
	v_add_u32_e32 v81, 0x4200, v80
	ds_write2_b32 v81, v94, v95 offset1:132
	v_add_u32_e32 v81, 0x4600, v80
	ds_write2_b32 v80, v86, v87 offset1:132
	ds_write2_b32 v81, v96, v97 offset0:8 offset1:140
	v_add_u32_e32 v81, 0x6200, v80
	v_add_u32_e32 v80, 0x6600, v80
	ds_write2_b32 v81, v114, v115 offset0:64 offset1:196
	ds_write2_b32 v80, v116, v117 offset0:72 offset1:204
	v_mul_lo_u32 v80, v195, s8
	v_lshlrev_b32_e32 v81, 2, v194
	s_waitcnt lgkmcnt(0)
	s_barrier
	v_add3_u32 v80, 0, v80, v81
	ds_read_b128 v[92:95], v80
	ds_read_b128 v[88:91], v80 offset:16
	ds_read_b128 v[84:87], v80 offset:32
	ds_read_b128 v[80:83], v80 offset:48
	s_cbranch_vccz .LBB0_2378
	s_mov_b64 s[38:39], 0
	s_and_b64 vcc, exec, s[36:37]
	s_mov_b64 s[36:37], 0
	s_cbranch_vccz .LBB0_2376
	s_waitcnt vmcnt(26)
	v_lshlrev_b32_e32 v96, 16, v12
	v_and_b32_e32 v97, 0xffff0000, v12
	v_lshlrev_b32_e32 v12, 16, v13
	v_and_b32_e32 v13, 0xffff0000, v13
	s_waitcnt lgkmcnt(3)
	v_pk_add_f32 v[122:123], v[94:95], v[12:13]
	v_lshlrev_b32_e32 v12, 16, v14
	v_and_b32_e32 v13, 0xffff0000, v14
	s_waitcnt lgkmcnt(2)
	v_pk_add_f32 v[124:125], v[88:89], v[12:13]
	v_lshlrev_b32_e32 v12, 16, v8
	v_and_b32_e32 v13, 0xffff0000, v8
	v_lshlrev_b32_e32 v8, 16, v9
	v_and_b32_e32 v9, 0xffff0000, v9
	v_pk_add_f32 v[120:121], v[92:93], v[96:97]
	s_waitcnt lgkmcnt(1)
	v_pk_add_f32 v[196:197], v[86:87], v[8:9]
	v_lshlrev_b32_e32 v8, 16, v10
	v_and_b32_e32 v9, 0xffff0000, v10
	v_lshlrev_b32_e32 v10, 16, v11
	v_and_b32_e32 v11, 0xffff0000, v11
	v_lshlrev_b32_e32 v14, 16, v15
	v_and_b32_e32 v15, 0xffff0000, v15
	s_waitcnt lgkmcnt(0)
	v_pk_add_f32 v[200:201], v[82:83], v[10:11]
	v_pk_add_f32 v[202:203], v[80:81], v[8:9]
	v_pk_mul_f32 v[8:9], v[122:123], v[122:123]
	v_pk_mul_f32 v[10:11], v[120:121], v[120:121]
	v_pk_add_f32 v[126:127], v[90:91], v[14:15]
	v_pk_add_f32 v[198:199], v[84:85], v[12:13]
	v_pk_mov_b32 v[12:13], v[10:11], v[8:9] op_sel:[1,0]
	v_mov_b32_e32 v11, v9
	v_pk_add_f32 v[8:9], v[12:13], v[10:11]
	v_pk_mul_f32 v[10:11], v[126:127], v[126:127]
	v_pk_mul_f32 v[12:13], v[124:125], v[124:125]
	v_pk_add_f32 v[8:9], v[8:9], v[8:9] op_sel:[0,1] op_sel_hi:[1,0]
	v_pk_mov_b32 v[14:15], v[12:13], v[10:11] op_sel:[1,0]
	v_mov_b32_e32 v13, v11
	v_pk_add_f32 v[10:11], v[14:15], v[12:13]
	v_mul_f32_e32 v12, v202, v202
	v_mul_f32_e32 v13, v203, v203
	v_pk_add_f32 v[10:11], v[10:11], v[10:11] op_sel:[0,1] op_sel_hi:[1,0]
	v_mov_b32_e32 v9, v12
	v_mov_b32_e32 v11, v13
	v_pk_add_f32 v[8:9], v[8:9], v[10:11]
	v_mul_f32_e32 v10, v199, v199
	v_mul_f32_e32 v12, v197, v197
	v_mul_f32_e32 v14, v200, v200
	v_mul_f32_e32 v15, v201, v201
	v_pk_fma_f32 v[10:11], v[198:199], v[198:199], v[10:11] op_sel_hi:[1,1,0]
	v_pk_fma_f32 v[12:13], v[196:197], v[196:197], v[12:13] op_sel_hi:[1,1,0]
	v_mov_b32_e32 v11, v14
	v_mov_b32_e32 v13, v15
	v_pk_add_f32 v[10:11], v[10:11], v[12:13]
	s_movk_i32 s8, 0x2800
	v_pk_add_f32 v[8:9], v[8:9], v[10:11]
	s_mov_b64 s[36:37], -1
	v_add_f32_e32 v8, v8, v9
	s_nop 1
	v_add_f32_dpp v8, v8, v8 quad_perm:[1,0,3,2] row_mask:0xf bank_mask:0xf bound_ctrl:1
	s_nop 1
	v_add_f32_dpp v8, v8, v8 quad_perm:[2,3,0,1] row_mask:0xf bank_mask:0xf bound_ctrl:1
	s_nop 1
	v_add_f32_dpp v8, v8, v8 row_half_mirror row_mask:0xf bank_mask:0xf bound_ctrl:1
	v_fmamk_f32 v8, v8, 0x3c000000, v165
	v_rsq_f32_e32 v204, v8
	v_mul_lo_u32 v8, v188, s8
	v_add_lshl_u32 v102, v8, v194, 1
	v_lshl_add_u32 v8, v194, 2, 0
	v_add_u32_e32 v116, 0x20000, v8
	ds_read_b128 v[8:11], v116
	ds_read_b128 v[12:15], v116 offset:16
	ds_read_b128 v[96:99], v116 offset:32
	ds_read_b128 v[116:119], v116 offset:48
	v_pk_mul_f32 v[120:121], v[120:121], v[204:205] op_sel_hi:[1,0]
	v_lshl_add_u64 v[114:115], s[90:91], 0, v[102:103]
	s_waitcnt lgkmcnt(3)
	v_pk_mul_f32 v[8:9], v[8:9], v[120:121]
	s_waitcnt vmcnt(24)
	v_lshlrev_b32_e32 v120, 16, v4
	v_and_b32_e32 v121, 0xffff0000, v4
	v_pk_mul_f32 v[8:9], v[8:9], v[120:121]
	v_pk_mul_f32 v[120:121], v[122:123], v[204:205] op_sel_hi:[1,0]
	v_lshlrev_b32_e32 v4, 16, v5
	v_pk_mul_f32 v[10:11], v[10:11], v[120:121]
	v_and_b32_e32 v5, 0xffff0000, v5
	v_pk_mul_f32 v[10:11], v[10:11], v[4:5]
	v_pk_mul_f32 v[4:5], v[124:125], v[204:205] op_sel_hi:[1,0]
	s_waitcnt lgkmcnt(2)
	v_pk_mul_f32 v[4:5], v[12:13], v[4:5]
	v_lshlrev_b32_e32 v12, 16, v6
	v_and_b32_e32 v13, 0xffff0000, v6
	v_pk_mul_f32 v[12:13], v[4:5], v[12:13]
	v_pk_mul_f32 v[4:5], v[126:127], v[204:205] op_sel_hi:[1,0]
	v_lshlrev_b32_e32 v6, 16, v7
	v_pk_mul_f32 v[4:5], v[14:15], v[4:5]
	v_and_b32_e32 v7, 0xffff0000, v7
	v_pk_mul_f32 v[14:15], v[4:5], v[6:7]
	v_cvt_pk_bf16_f32 v4, v8, v9
	v_cvt_pk_bf16_f32 v5, v10, v11
	v_cvt_pk_bf16_f32 v6, v12, v13
	v_cvt_pk_bf16_f32 v7, v14, v15
	global_store_dwordx4 v102, v[4:7], s[90:91]
	v_lshlrev_b32_e32 v8, 16, v2
	v_and_b32_e32 v9, 0xffff0000, v2
	v_pk_mul_f32 v[4:5], v[198:199], v[204:205] op_sel_hi:[1,0]
	v_lshlrev_b32_e32 v6, 16, v0
	s_waitcnt lgkmcnt(1)
	v_pk_mul_f32 v[4:5], v[96:97], v[4:5]
	v_and_b32_e32 v7, 0xffff0000, v0
	v_pk_mul_f32 v[4:5], v[4:5], v[6:7]
	v_pk_mul_f32 v[6:7], v[196:197], v[204:205] op_sel_hi:[1,0]
	v_lshlrev_b32_e32 v0, 16, v1
	v_pk_mul_f32 v[6:7], v[98:99], v[6:7]
	v_and_b32_e32 v1, 0xffff0000, v1
	v_pk_mul_f32 v[0:1], v[6:7], v[0:1]
	v_pk_mul_f32 v[6:7], v[202:203], v[204:205] op_sel_hi:[1,0]
	v_lshlrev_b32_e32 v2, 16, v3
	s_waitcnt lgkmcnt(0)
	v_pk_mul_f32 v[6:7], v[6:7], v[116:117]
	v_and_b32_e32 v3, 0xffff0000, v3
	v_pk_mul_f32 v[6:7], v[6:7], v[8:9]
	v_pk_mul_f32 v[8:9], v[200:201], v[204:205] op_sel_hi:[1,0]
	v_cvt_pk_bf16_f32 v96, v4, v5
	v_pk_mul_f32 v[8:9], v[8:9], v[118:119]
	v_cvt_pk_bf16_f32 v97, v0, v1
	v_pk_mul_f32 v[116:117], v[8:9], v[2:3]
	v_cvt_pk_bf16_f32 v98, v6, v7
	s_and_b64 vcc, exec, s[38:39]
	s_cbranch_vccz .LBB0_2379
	s_branch .LBB0_2377
